# ATTN fast tail: the 4 trans-hazard s_nop pads per step replaced by moving the chunk's first cvt_pk into the slot
# speedup vs baseline: 1.0068x; 1.0068x over previous
.Lfa_norescale:
	v_fmamk_f32 v0, v0, 0x3fb8aa3b, v36
	v_fmamk_f32 v1, v1, 0x3fb8aa3b, v36
	v_fmamk_f32 v2, v2, 0x3fb8aa3b, v36
	v_fmamk_f32 v3, v3, 0x3fb8aa3b, v36
	v_fmamk_f32 v4, v4, 0x3fb8aa3b, v36
	v_fmamk_f32 v5, v5, 0x3fb8aa3b, v36
	v_fmamk_f32 v6, v6, 0x3fb8aa3b, v36
	v_fmamk_f32 v7, v7, 0x3fb8aa3b, v36
	v_exp_f32_e32 v0, v0
	v_exp_f32_e32 v1, v1
	v_add_f32_e32 v37, v0, v37
	v_exp_f32_e32 v2, v2
	v_add_f32_e32 v37, v1, v37
	v_exp_f32_e32 v3, v3
	v_add_f32_e32 v37, v2, v37
	v_exp_f32_e32 v4, v4
	v_add_f32_e32 v37, v3, v37
	v_exp_f32_e32 v5, v5
	v_add_f32_e32 v37, v4, v37
	v_exp_f32_e32 v6, v6
	v_add_f32_e32 v37, v5, v37
	v_exp_f32_e32 v7, v7
	v_add_f32_e32 v37, v6, v37
	v_cvt_pk_bf16_f32 v0, v0, v1
	v_add_f32_e32 v37, v7, v37
	v_cvt_pk_bf16_f32 v1, v2, v3
	v_cvt_pk_bf16_f32 v2, v4, v5
	v_cvt_pk_bf16_f32 v3, v6, v7
	s_waitcnt lgkmcnt(14)
	v_fmamk_f32 v8, v8, 0x3fb8aa3b, v36
	v_mfma_f32_32x32x16_bf16 v[64:79], v[134:137], v[0:3], v[64:79]
	s_waitcnt lgkmcnt(12)
	v_mfma_f32_32x32x16_bf16 v[48:63], v[138:141], v[0:3], v[48:63]
	v_fmamk_f32 v9, v9, 0x3fb8aa3b, v36
	v_fmamk_f32 v10, v10, 0x3fb8aa3b, v36
	v_fmamk_f32 v11, v11, 0x3fb8aa3b, v36
	v_fmamk_f32 v12, v12, 0x3fb8aa3b, v36
	v_fmamk_f32 v13, v13, 0x3fb8aa3b, v36
	v_fmamk_f32 v14, v14, 0x3fb8aa3b, v36
	v_fmamk_f32 v15, v15, 0x3fb8aa3b, v36
	v_exp_f32_e32 v8, v8
	v_exp_f32_e32 v9, v9
	v_add_f32_e32 v37, v8, v37
	v_exp_f32_e32 v10, v10
	v_add_f32_e32 v37, v9, v37
	v_exp_f32_e32 v11, v11
	v_add_f32_e32 v37, v10, v37
	v_exp_f32_e32 v12, v12
	v_add_f32_e32 v37, v11, v37
	v_exp_f32_e32 v13, v13
	v_add_f32_e32 v37, v12, v37
	v_exp_f32_e32 v14, v14
	v_add_f32_e32 v37, v13, v37
	v_exp_f32_e32 v15, v15
	v_add_f32_e32 v37, v14, v37
	v_cvt_pk_bf16_f32 v8, v8, v9
	v_add_f32_e32 v37, v15, v37
	v_cvt_pk_bf16_f32 v9, v10, v11
	v_cvt_pk_bf16_f32 v10, v12, v13
	v_cvt_pk_bf16_f32 v11, v14, v15
	s_waitcnt lgkmcnt(10)
	v_fmamk_f32 v16, v16, 0x3fb8aa3b, v36
	v_mfma_f32_32x32x16_bf16 v[64:79], v[142:145], v[8:11], v[64:79]
	s_waitcnt lgkmcnt(8)
	v_mfma_f32_32x32x16_bf16 v[48:63], v[146:149], v[8:11], v[48:63]
	v_fmamk_f32 v17, v17, 0x3fb8aa3b, v36
	v_fmamk_f32 v18, v18, 0x3fb8aa3b, v36
	v_fmamk_f32 v19, v19, 0x3fb8aa3b, v36
	v_fmamk_f32 v20, v20, 0x3fb8aa3b, v36
	v_fmamk_f32 v21, v21, 0x3fb8aa3b, v36
	v_fmamk_f32 v22, v22, 0x3fb8aa3b, v36
	v_fmamk_f32 v23, v23, 0x3fb8aa3b, v36
	v_exp_f32_e32 v16, v16
	v_exp_f32_e32 v17, v17
	v_add_f32_e32 v37, v16, v37
	v_exp_f32_e32 v18, v18
	v_add_f32_e32 v37, v17, v37
	v_exp_f32_e32 v19, v19
	v_add_f32_e32 v37, v18, v37
	v_exp_f32_e32 v20, v20
	v_add_f32_e32 v37, v19, v37
	v_exp_f32_e32 v21, v21
	v_add_f32_e32 v37, v20, v37
	v_exp_f32_e32 v22, v22
	v_add_f32_e32 v37, v21, v37
	v_exp_f32_e32 v23, v23
	v_add_f32_e32 v37, v22, v37
	v_cvt_pk_bf16_f32 v16, v16, v17
	v_add_f32_e32 v37, v23, v37
	v_cvt_pk_bf16_f32 v17, v18, v19
	v_cvt_pk_bf16_f32 v18, v20, v21
	v_cvt_pk_bf16_f32 v19, v22, v23
	s_waitcnt lgkmcnt(6)
	v_fmamk_f32 v24, v24, 0x3fb8aa3b, v36
	v_mfma_f32_32x32x16_bf16 v[64:79], v[236:239], v[16:19], v[64:79]
	s_waitcnt lgkmcnt(4)
	v_mfma_f32_32x32x16_bf16 v[48:63], v[240:243], v[16:19], v[48:63]
	v_fmamk_f32 v25, v25, 0x3fb8aa3b, v36
	v_fmamk_f32 v26, v26, 0x3fb8aa3b, v36
	v_fmamk_f32 v27, v27, 0x3fb8aa3b, v36
	v_fmamk_f32 v28, v28, 0x3fb8aa3b, v36
	v_fmamk_f32 v29, v29, 0x3fb8aa3b, v36
	v_fmamk_f32 v30, v30, 0x3fb8aa3b, v36
	v_fmamk_f32 v31, v31, 0x3fb8aa3b, v36
	v_exp_f32_e32 v24, v24
	v_exp_f32_e32 v25, v25
	v_add_f32_e32 v37, v24, v37
	v_exp_f32_e32 v26, v26
	v_add_f32_e32 v37, v25, v37
	v_exp_f32_e32 v27, v27
	v_add_f32_e32 v37, v26, v37
	v_exp_f32_e32 v28, v28
	v_add_f32_e32 v37, v27, v37
	v_exp_f32_e32 v29, v29
	v_add_f32_e32 v37, v28, v37
	v_exp_f32_e32 v30, v30
	v_add_f32_e32 v37, v29, v37
	v_exp_f32_e32 v31, v31
	v_add_f32_e32 v37, v30, v37
	v_cvt_pk_bf16_f32 v24, v24, v25
	v_add_f32_e32 v37, v31, v37
	v_cvt_pk_bf16_f32 v25, v26, v27
	v_cvt_pk_bf16_f32 v26, v28, v29
	v_cvt_pk_bf16_f32 v27, v30, v31
	s_waitcnt lgkmcnt(2)
	s_nop 0
	v_mfma_f32_32x32x16_bf16 v[64:79], v[244:247], v[24:27], v[64:79]
	s_waitcnt lgkmcnt(0)
	v_mfma_f32_32x32x16_bf16 v[48:63], v[248:251], v[24:27], v[48:63]
	v_fmac_f32_e32 v37, v121, v34
	v_mov_b32_e32 v123, v33
	v_mov_b32_e32 v121, v37
	s_branch .LBB0_1470
